# w_in phase round 2: 140 of the otherwise idle workgroups run plain attention-side w_in units taken from the mixer queue (170 made the phase itself longer)
# speedup vs baseline: 1.0128x; 1.0021x over previous
.Lwsteal:
	s_cmp_lg_u32 s25, 0
	s_cbranch_scc1 .LBB0_236
	s_add_i32 s5, s24, 0xfffffeaa
	s_cmpk_lt_u32 s5, 0x8c
	s_cbranch_scc0 .LBB0_236
	s_add_i32 s5, s5, 0x74
	s_lshr_b32 s20, s5, 2
	s_and_b32 s21, s5, 3
	s_min_u32 s5, s21, 1
	s_add_i32 s21, s21, s5
	s_add_i32 s5, s21, 5
	s_cmp_lt_u32 s21, 4
	s_cselect_b32 s22, s21, s5
	s_mov_b64 s[2:3], -1

.LBB0_671:
	s_or_b64 exec, exec, s[2:3]
	s_waitcnt vmcnt(0)
	v_readfirstlane_b32 s2, v2
	s_mov_b64 s[8:9], s[72:73]
	s_nop 0
	v_add_u32_e32 v0, s2, v0
	v_add_u32_e32 v2, 0x8c, v0
	v_cmp_lt_i32_e32 vcc, 0xf3, v0
	s_nop 1
	v_cndmask_b32_e32 v0, v0, v2, vcc
	v_cmp_gt_i32_e32 vcc, s62, v0
	v_cmp_le_i32_e64 s[2:3], s85, v0
	s_or_b64 s[4:5], vcc, s[2:3]
	s_nor_b64 s[10:11], s[4:5], s[72:73]
	s_and_saveexec_b64 s[4:5], s[10:11]
	s_cbranch_execz .LBB0_686
	s_mov_b32 s10, 0x1000000
	s_branch .LBB0_675

.LBB0_675:
	global_load_dword v2, v1, s[90:91] offset:192 sc1
	s_mov_b64 s[8:9], -1
	s_waitcnt vmcnt(0)
	v_cmp_lt_u32_e32 vcc, 0xf3, v2
	s_cbranch_vccnz .LBB0_674
	s_cmp_lg_u32 s10, 0
	s_sleep 2
	s_cbranch_scc0 .LBB0_673
	global_load_dword v2, v1, s[90:91] offset:192 sc1
	s_waitcnt vmcnt(0)
	v_cmp_gt_u32_e32 vcc, 0xf4, v2
	s_cbranch_vccz .LBB0_674
	s_sleep 2
	global_load_dword v2, v1, s[90:91] offset:192 sc1
	s_waitcnt vmcnt(0)
	v_cmp_gt_u32_e32 vcc, 0xf4, v2
	s_cbranch_vccz .LBB0_674
	s_sleep 2
	global_load_dword v2, v1, s[90:91] offset:192 sc1
	s_waitcnt vmcnt(0)
	v_cmp_gt_u32_e32 vcc, 0xf4, v2
	s_cbranch_vccz .LBB0_674
	s_sleep 2
	global_load_dword v2, v1, s[90:91] offset:192 sc1
	s_waitcnt vmcnt(0)
	v_cmp_gt_u32_e32 vcc, 0xf4, v2
	s_cbranch_vccz .LBB0_674
	s_sleep 2
	global_load_dword v2, v1, s[90:91] offset:192 sc1
	s_waitcnt vmcnt(0)
	v_cmp_gt_u32_e32 vcc, 0xf4, v2
	s_cbranch_vccz .LBB0_674
	s_sleep 2
	global_load_dword v2, v1, s[90:91] offset:192 sc1
	s_waitcnt vmcnt(0)
	v_cmp_gt_u32_e32 vcc, 0xf4, v2
	s_cbranch_vccz .LBB0_674
	s_sleep 2
	global_load_dword v2, v1, s[90:91] offset:192 sc1
	s_waitcnt vmcnt(0)
	v_cmp_gt_u32_e32 vcc, 0xf4, v2
	s_cbranch_vccz .LBB0_674
	s_sleep 2
	s_add_i32 s10, s10, -8
	s_mov_b64 s[8:9], 0
	s_branch .LBB0_674
